# scalar-base LDS-DMA loads extended to the up-projection K-loop (vcc/s-pair saddr, 16 more VALU removed)
# baseline (speedup 1.0000x reference)
; #define PG8_STAGE(bufoff, gbase, voff) do { _Pragma("unroll") for (int _i = 0; _i < 2; ++_i) \
;         __builtin_amdgcn_global_load_lds((const unsigned*)((const char*)(gbase) + (voff)[_i]), (LAS unsigned*)(lds + (bufoff) + ldsw + _i * 8192), 16, 0, 0); } while (0)
; #define PG8_LDA(dst, b, h) do { _Pragma("unroll") for (int m = 0; m < 4; ++m) _Pragma("unroll") for (int k = 0; k < 2; ++k) dst[m][k] = *(const LAS bf16x8*)(lds + PG8_SA(b, h) + aoff + m * 2048 + k * 1024); } while (0)
; #define PG8_LDB(dst, b, h) do { _Pragma("unroll") for (int n = 0; n < 2; ++n) _Pragma("unroll") for (int k = 0; k < 2; ++k) dst[n][k] = *(const LAS bf16x8*)(lds + PG8_SB(b, h) + boff + n * 2048 + k * 1024); } while (0)
; #define PG8_WAIT_V(n) asm volatile("s_waitcnt vmcnt(" #n ")" ::: "memory")
; #define PG8_WAIT_L(n) asm volatile("s_waitcnt lgkmcnt(" #n ")" ::: "memory")
; #define PG8_BAR __builtin_amdgcn_s_barrier()
; #define PG8_SCHED __builtin_amdgcn_sched_barrier(0)
; template <class Epi, class Sched>
; DI void gemm_phase(LAS unsigned char* lds, const Sched& S, const Epi& E) {
;     ...
;     for (int t = 0; t < nt; t += 2) {
;       const bool last = (t == nt - 2);
;       const char* a1 = cA + (size_t)(t + 1) * kstep;
;       const char* a2 = last ? nA : cA + (size_t)(t + 2) * kstep; const char* b2 = last ? nB : cB + (size_t)(t + 2) * kstep;
;       const char* a3 = a2 + kstep; const char* b3 = b2 + kstep;
;       PG8_LDB(B0, 0, 0); PG8_LDB(B1, 0, 1); PG8_SCHED; PG8_LDA(At, 0, 0); PG8_STAGE(PG8_SA(1, 1), a1 + hstep, voffA);
;       PG8_WAIT_V(8); PG8_WAIT_L(0); PG8_BAR; PG8_MMA(0, 0, At, B0); PG8_MMA(0, 1, At, B1); PG8_BAR; PG8_SCHED;
;       PG8_LDA(At, 0, 1); PG8_STAGE(PG8_SB(0, 0), b2, voffB); PG8_STAGE(PG8_SB(0, 1), b2 + hstep, voffB); PG8_STAGE(PG8_SA(0, 0), a2, voffA);
;       PG8_WAIT_V(8); PG8_WAIT_L(0); PG8_BAR; PG8_MMA(1, 0, At, B0); PG8_MMA(1, 1, At, B1); PG8_BAR; PG8_SCHED;
;       PG8_LDB(B0, 1, 0); PG8_LDB(B1, 1, 1); PG8_SCHED; PG8_LDA(At, 1, 0); PG8_STAGE(PG8_SA(0, 1), a2 + hstep, voffA);
;       PG8_WAIT_V(8); PG8_WAIT_L(0); PG8_BAR; PG8_MMA(0, 0, At, B0); PG8_MMA(0, 1, At, B1); PG8_BAR; PG8_SCHED;
;       PG8_LDA(At, 1, 1); PG8_STAGE(PG8_SB(1, 0), b3, voffB); PG8_STAGE(PG8_SB(1, 1), b3 + hstep, voffB); PG8_STAGE(PG8_SA(1, 0), a3, voffA);
;       PG8_WAIT_V(8); PG8_WAIT_L(0); PG8_BAR; PG8_MMA(1, 0, At, B0); PG8_MMA(1, 1, At, B1); PG8_BAR; PG8_SCHED;
;     }
.LBB0_479:
	s_add_u32 s22, vcc_lo, 0xfff80080
	s_addc_u32 s23, vcc_hi, -1
	s_add_i32 s80, 0, 0x10000
	s_cmp_eq_u32 s79, 28
	s_cselect_b32 s27, s44, s23
	s_cselect_b32 s26, s45, s22
	s_cselect_b32 s23, s67, s78
	s_cselect_b32 s22, s76, s77
	s_add_i32 s82, 0, 0x14000
	v_add_u32_e32 v44, s80, v167
	v_add_u32_e32 v68, s82, v167
	ds_read_b128 v[24:27], v44
	ds_read_b128 v[36:39], v44 offset:1024
	ds_read_b128 v[40:43], v44 offset:2048
	ds_read_b128 v[44:47], v44 offset:3072
	ds_read_b128 v[52:55], v68
	ds_read_b128 v[60:63], v68 offset:1024
	ds_read_b128 v[64:67], v68 offset:2048
	ds_read_b128 v[68:71], v68 offset:3072
	s_add_i32 m0, s51, 0xc000
	ds_read_b128 v[174:177], v195
	ds_read_b128 v[178:181], v195 offset:1024
	ds_read_b128 v[182:185], v195 offset:2048
	ds_read_b128 v[186:189], v195 offset:3072
	ds_read_b128 v[190:193], v195 offset:4096
	ds_read_b128 v[196:199], v195 offset:5120
	ds_read_b128 v[200:203], v195 offset:6144
	ds_read_b128 v[204:207], v195 offset:7168
	global_load_lds_dwordx4 v170, vcc
	s_add_i32 m0, s51, 0xe000
	s_nop 0
	global_load_lds_dwordx4 v172, vcc
	s_waitcnt vmcnt(8) lgkmcnt(0)
	s_setprio 1
	s_barrier
	v_mfma_f32_16x16x32_bf16 v[156:159], v[24:27], v[174:177], v[156:159]
	v_mfma_f32_16x16x32_bf16 v[152:155], v[40:43], v[174:177], v[152:155]
	v_mfma_f32_16x16x32_bf16 v[148:151], v[24:27], v[182:185], v[148:151]
	v_mfma_f32_16x16x32_bf16 v[140:143], v[40:43], v[182:185], v[140:143]
	v_mfma_f32_16x16x32_bf16 v[128:131], v[24:27], v[190:193], v[128:131]
	v_mfma_f32_16x16x32_bf16 v[120:123], v[40:43], v[190:193], v[120:123]
	v_mfma_f32_16x16x32_bf16 v[112:115], v[24:27], v[200:203], v[112:115]
	v_mfma_f32_16x16x32_bf16 v[104:107], v[40:43], v[200:203], v[104:107]
	v_mfma_f32_16x16x32_bf16 v[156:159], v[36:39], v[178:181], v[156:159]
	v_mfma_f32_16x16x32_bf16 v[152:155], v[44:47], v[178:181], v[152:155]
	v_mfma_f32_16x16x32_bf16 v[148:151], v[36:39], v[186:189], v[148:151]
	v_mfma_f32_16x16x32_bf16 v[140:143], v[44:47], v[186:189], v[140:143]
	v_mfma_f32_16x16x32_bf16 v[128:131], v[36:39], v[196:199], v[128:131]
	v_mfma_f32_16x16x32_bf16 v[120:123], v[44:47], v[196:199], v[120:123]
	v_mfma_f32_16x16x32_bf16 v[112:115], v[36:39], v[204:207], v[112:115]
	v_mfma_f32_16x16x32_bf16 v[104:107], v[44:47], v[204:207], v[104:107]
	v_mfma_f32_16x16x32_bf16 v[144:147], v[52:55], v[174:177], v[144:147]
	v_mfma_f32_16x16x32_bf16 v[136:139], v[64:67], v[174:177], v[136:139]
	v_mfma_f32_16x16x32_bf16 v[124:127], v[52:55], v[182:185], v[124:127]
	v_mfma_f32_16x16x32_bf16 v[132:135], v[64:67], v[182:185], v[132:135]
	v_mfma_f32_16x16x32_bf16 v[108:111], v[52:55], v[190:193], v[108:111]
	v_mfma_f32_16x16x32_bf16 v[116:119], v[64:67], v[190:193], v[116:119]
	v_mfma_f32_16x16x32_bf16 v[96:99], v[52:55], v[200:203], v[96:99]
	v_mfma_f32_16x16x32_bf16 v[100:103], v[64:67], v[200:203], v[100:103]
	v_mfma_f32_16x16x32_bf16 v[144:147], v[60:63], v[178:181], v[144:147]
	v_mfma_f32_16x16x32_bf16 v[136:139], v[68:71], v[178:181], v[136:139]
	v_mfma_f32_16x16x32_bf16 v[124:127], v[60:63], v[186:189], v[124:127]
	v_mfma_f32_16x16x32_bf16 v[132:135], v[68:71], v[186:189], v[132:135]
	v_mfma_f32_16x16x32_bf16 v[108:111], v[60:63], v[196:199], v[108:111]
	v_mfma_f32_16x16x32_bf16 v[116:119], v[68:71], v[196:199], v[116:119]
	v_mfma_f32_16x16x32_bf16 v[96:99], v[60:63], v[204:207], v[96:99]
	v_mfma_f32_16x16x32_bf16 v[100:103], v[68:71], v[204:207], v[100:103]
	s_barrier
	s_add_u32 s48, s22, s6
	s_addc_u32 s49, s23, s7
	s_add_u32 s98, s26, s6
	s_addc_u32 s99, s27, s7
	s_setprio 0
	s_add_i32 s80, s80, s47
	s_mov_b32 m0, s80
	ds_read_b128 v[174:177], v195 offset:16384
	ds_read_b128 v[178:181], v195 offset:17408
	ds_read_b128 v[182:185], v195 offset:18432
	ds_read_b128 v[186:189], v195 offset:19456
	ds_read_b128 v[190:193], v195 offset:20480
	ds_read_b128 v[196:199], v195 offset:21504
	ds_read_b128 v[200:203], v195 offset:22528
	ds_read_b128 v[204:207], v195 offset:23552
	global_load_lds_dwordx4 v208, s[22:23]
	s_add_i32 m0, s80, 0x2000
	s_add_u32 s80, s22, 0x80000
	s_addc_u32 s81, s23, 0
	s_add_i32 s82, s82, s47
	global_load_lds_dwordx4 v160, s[22:23]
	s_mov_b32 m0, s82
	s_nop 0
	global_load_lds_dwordx4 v208, s[80:81]
	s_add_i32 m0, s82, 0x2000
	s_nop 0
	global_load_lds_dwordx4 v160, s[80:81]
	s_mov_b32 m0, s51
	s_nop 0
	global_load_lds_dwordx4 v164, s[26:27]
	s_mov_b32 m0, s54
	s_nop 0
	global_load_lds_dwordx4 v162, s[26:27]
	s_waitcnt vmcnt(8) lgkmcnt(0)
	s_setprio 1
	s_barrier
	v_mfma_f32_16x16x32_bf16 v[92:95], v[24:27], v[174:177], v[92:95]
	v_mfma_f32_16x16x32_bf16 v[88:91], v[40:43], v[174:177], v[88:91]
	v_mfma_f32_16x16x32_bf16 v[84:87], v[24:27], v[182:185], v[84:87]
	v_mfma_f32_16x16x32_bf16 v[76:79], v[40:43], v[182:185], v[76:79]
	v_mfma_f32_16x16x32_bf16 v[48:51], v[24:27], v[190:193], v[48:51]
	v_mfma_f32_16x16x32_bf16 v[28:31], v[40:43], v[190:193], v[28:31]
	v_mfma_f32_16x16x32_bf16 v[16:19], v[24:27], v[200:203], v[16:19]
	v_mfma_f32_16x16x32_bf16 v[8:11], v[40:43], v[200:203], v[8:11]
	v_mfma_f32_16x16x32_bf16 v[92:95], v[36:39], v[178:181], v[92:95]
	v_mfma_f32_16x16x32_bf16 v[88:91], v[44:47], v[178:181], v[88:91]
	v_mfma_f32_16x16x32_bf16 v[84:87], v[36:39], v[186:189], v[84:87]
	v_mfma_f32_16x16x32_bf16 v[76:79], v[44:47], v[186:189], v[76:79]
	v_mfma_f32_16x16x32_bf16 v[48:51], v[36:39], v[196:199], v[48:51]
	v_mfma_f32_16x16x32_bf16 v[28:31], v[44:47], v[196:199], v[28:31]
	v_mfma_f32_16x16x32_bf16 v[16:19], v[36:39], v[204:207], v[16:19]
	v_mfma_f32_16x16x32_bf16 v[8:11], v[44:47], v[204:207], v[8:11]
	v_mfma_f32_16x16x32_bf16 v[32:35], v[52:55], v[182:185], v[32:35]
	v_mfma_f32_16x16x32_bf16 v[12:15], v[52:55], v[190:193], v[12:15]
	v_mfma_f32_16x16x32_bf16 v[20:23], v[64:67], v[190:193], v[20:23]
	v_mfma_f32_16x16x32_bf16 v[0:3], v[52:55], v[200:203], v[0:3]
	v_mfma_f32_16x16x32_bf16 v[4:7], v[64:67], v[200:203], v[4:7]
	v_mfma_f32_16x16x32_bf16 v[24:27], v[52:55], v[174:177], v[80:83]
	v_mfma_f32_16x16x32_bf16 v[36:39], v[64:67], v[174:177], v[72:75]
	v_mfma_f32_16x16x32_bf16 v[32:35], v[60:63], v[186:189], v[32:35]
	v_mfma_f32_16x16x32_bf16 v[40:43], v[64:67], v[182:185], v[56:59]
	v_mfma_f32_16x16x32_bf16 v[12:15], v[60:63], v[196:199], v[12:15]
	v_mfma_f32_16x16x32_bf16 v[20:23], v[68:71], v[196:199], v[20:23]
	v_mfma_f32_16x16x32_bf16 v[0:3], v[60:63], v[204:207], v[0:3]
	v_mfma_f32_16x16x32_bf16 v[4:7], v[68:71], v[204:207], v[4:7]
	v_mfma_f32_16x16x32_bf16 v[24:27], v[60:63], v[178:181], v[24:27]
	v_mfma_f32_16x16x32_bf16 v[36:39], v[68:71], v[178:181], v[36:39]
	v_mfma_f32_16x16x32_bf16 v[40:43], v[68:71], v[186:189], v[40:43]
	s_barrier
; #define PG8_STAGE(bufoff, gbase, voff) do { _Pragma("unroll") for (int _i = 0; _i < 2; ++_i) \
;         __builtin_amdgcn_global_load_lds((const unsigned*)((const char*)(gbase) + (voff)[_i]), (LAS unsigned*)(lds + (bufoff) + ldsw + _i * 8192), 16, 0, 0); } while (0)
; #define PG8_LDA(dst, b, h) do { _Pragma("unroll") for (int m = 0; m < 4; ++m) _Pragma("unroll") for (int k = 0; k < 2; ++k) dst[m][k] = *(const LAS bf16x8*)(lds + PG8_SA(b, h) + aoff + m * 2048 + k * 1024); } while (0)
; #define PG8_LDB(dst, b, h) do { _Pragma("unroll") for (int n = 0; n < 2; ++n) _Pragma("unroll") for (int k = 0; k < 2; ++k) dst[n][k] = *(const LAS bf16x8*)(lds + PG8_SB(b, h) + boff + n * 2048 + k * 1024); } while (0)
; #define PG8_WAIT_V(n) asm volatile("s_waitcnt vmcnt(" #n ")" ::: "memory")
; #define PG8_WAIT_L(n) asm volatile("s_waitcnt lgkmcnt(" #n ")" ::: "memory")
; #define PG8_BAR __builtin_amdgcn_s_barrier()
; #define PG8_SCHED __builtin_amdgcn_sched_barrier(0)
; template <class Epi, class Sched>
; DI void gemm_phase(LAS unsigned char* lds, const Sched& S, const Epi& E) {
;     ...
;     for (int t = 0; t < nt; t += 2) {
;       const bool last = (t == nt - 2);
;       const char* a1 = cA + (size_t)(t + 1) * kstep;
;       const char* a2 = last ? nA : cA + (size_t)(t + 2) * kstep; const char* b2 = last ? nB : cB + (size_t)(t + 2) * kstep;
;       const char* a3 = a2 + kstep; const char* b3 = b2 + kstep;
;       PG8_LDB(B0, 0, 0); PG8_LDB(B1, 0, 1); PG8_SCHED; PG8_LDA(At, 0, 0); PG8_STAGE(PG8_SA(1, 1), a1 + hstep, voffA);
;       PG8_WAIT_V(8); PG8_WAIT_L(0); PG8_BAR; PG8_MMA(0, 0, At, B0); PG8_MMA(0, 1, At, B1); PG8_BAR; PG8_SCHED;
;       PG8_LDA(At, 0, 1); PG8_STAGE(PG8_SB(0, 0), b2, voffB); PG8_STAGE(PG8_SB(0, 1), b2 + hstep, voffB); PG8_STAGE(PG8_SA(0, 0), a2, voffA);
;       PG8_WAIT_V(8); PG8_WAIT_L(0); PG8_BAR; PG8_MMA(1, 0, At, B0); PG8_MMA(1, 1, At, B1); PG8_BAR; PG8_SCHED;
;       PG8_LDB(B0, 1, 0); PG8_LDB(B1, 1, 1); PG8_SCHED; PG8_LDA(At, 1, 0); PG8_STAGE(PG8_SA(0, 1), a2 + hstep, voffA);
;       PG8_WAIT_V(8); PG8_WAIT_L(0); PG8_BAR; PG8_MMA(0, 0, At, B0); PG8_MMA(0, 1, At, B1); PG8_BAR; PG8_SCHED;
;       PG8_LDA(At, 1, 1); PG8_STAGE(PG8_SB(1, 0), b3, voffB); PG8_STAGE(PG8_SB(1, 1), b3 + hstep, voffB); PG8_STAGE(PG8_SA(1, 0), a3, voffA);
;       PG8_WAIT_V(8); PG8_WAIT_L(0); PG8_BAR; PG8_MMA(1, 0, At, B0); PG8_MMA(1, 1, At, B1); PG8_BAR; PG8_SCHED;
;     }
	s_setprio 0
	s_add_i32 s80, 0, 0x18000
	s_add_i32 s81, 0, 0x1c000
	v_add_u32_e32 v60, s80, v167
	v_add_u32_e32 v72, s81, v167
	ds_read_b128 v[44:47], v60
	ds_read_b128 v[52:55], v60 offset:1024
	ds_read_b128 v[56:59], v60 offset:2048
	ds_read_b128 v[60:63], v60 offset:3072
	ds_read_b128 v[64:67], v72
	ds_read_b128 v[68:71], v72 offset:1024
	ds_read_b128 v[174:177], v72 offset:2048
	ds_read_b128 v[178:181], v72 offset:3072
	s_add_u32 s26, s26, 0x80000
	s_addc_u32 s27, s27, 0
	s_mov_b32 m0, s55
	ds_read_b128 v[72:75], v195 offset:32768
	ds_read_b128 v[80:83], v195 offset:33792
	ds_read_b128 v[182:185], v195 offset:34816
	ds_read_b128 v[186:189], v195 offset:35840
	ds_read_b128 v[190:193], v195 offset:36864
	ds_read_b128 v[196:199], v195 offset:37888
	ds_read_b128 v[200:203], v195 offset:38912
	ds_read_b128 v[204:207], v195 offset:39936
	global_load_lds_dwordx4 v164, s[26:27]
	s_mov_b32 m0, s72
	s_nop 0
	global_load_lds_dwordx4 v162, s[26:27]
	s_waitcnt vmcnt(8) lgkmcnt(0)
	s_setprio 1
	s_barrier
	v_mfma_f32_16x16x32_bf16 v[156:159], v[44:47], v[72:75], v[156:159]
	v_mfma_f32_16x16x32_bf16 v[152:155], v[56:59], v[72:75], v[152:155]
	v_mfma_f32_16x16x32_bf16 v[148:151], v[44:47], v[182:185], v[148:151]
	v_mfma_f32_16x16x32_bf16 v[140:143], v[56:59], v[182:185], v[140:143]
	v_mfma_f32_16x16x32_bf16 v[128:131], v[44:47], v[190:193], v[128:131]
	v_mfma_f32_16x16x32_bf16 v[120:123], v[56:59], v[190:193], v[120:123]
	v_mfma_f32_16x16x32_bf16 v[112:115], v[44:47], v[200:203], v[112:115]
	v_mfma_f32_16x16x32_bf16 v[104:107], v[56:59], v[200:203], v[104:107]
	v_mfma_f32_16x16x32_bf16 v[156:159], v[52:55], v[80:83], v[156:159]
	v_mfma_f32_16x16x32_bf16 v[152:155], v[60:63], v[80:83], v[152:155]
	v_mfma_f32_16x16x32_bf16 v[148:151], v[52:55], v[186:189], v[148:151]
	v_mfma_f32_16x16x32_bf16 v[140:143], v[60:63], v[186:189], v[140:143]
	v_mfma_f32_16x16x32_bf16 v[128:131], v[52:55], v[196:199], v[128:131]
	v_mfma_f32_16x16x32_bf16 v[120:123], v[60:63], v[196:199], v[120:123]
	v_mfma_f32_16x16x32_bf16 v[112:115], v[52:55], v[204:207], v[112:115]
	v_mfma_f32_16x16x32_bf16 v[104:107], v[60:63], v[204:207], v[104:107]
	v_mfma_f32_16x16x32_bf16 v[144:147], v[64:67], v[72:75], v[144:147]
	v_mfma_f32_16x16x32_bf16 v[72:75], v[174:177], v[72:75], v[136:139]
	v_mfma_f32_16x16x32_bf16 v[136:139], v[178:181], v[80:83], v[72:75]
	v_mfma_f32_16x16x32_bf16 v[72:75], v[64:67], v[182:185], v[124:127]
	v_mfma_f32_16x16x32_bf16 v[124:127], v[68:71], v[186:189], v[72:75]
	v_mfma_f32_16x16x32_bf16 v[72:75], v[174:177], v[182:185], v[132:135]
	v_mfma_f32_16x16x32_bf16 v[132:135], v[178:181], v[186:189], v[72:75]
	v_mfma_f32_16x16x32_bf16 v[72:75], v[64:67], v[190:193], v[108:111]
	v_mfma_f32_16x16x32_bf16 v[108:111], v[68:71], v[196:199], v[72:75]
	v_mfma_f32_16x16x32_bf16 v[72:75], v[174:177], v[190:193], v[116:119]
	v_mfma_f32_16x16x32_bf16 v[116:119], v[178:181], v[196:199], v[72:75]
	v_mfma_f32_16x16x32_bf16 v[72:75], v[64:67], v[200:203], v[96:99]
	v_mfma_f32_16x16x32_bf16 v[96:99], v[68:71], v[204:207], v[72:75]
	v_mfma_f32_16x16x32_bf16 v[72:75], v[174:177], v[200:203], v[100:103]
	v_mfma_f32_16x16x32_bf16 v[144:147], v[68:71], v[80:83], v[144:147]
	v_mfma_f32_16x16x32_bf16 v[100:103], v[178:181], v[204:207], v[72:75]
	s_barrier
	s_setprio 0
	s_add_i32 s26, s80, s47
	s_mov_b32 m0, s26
	s_nop 0
	ds_read_b128 v[72:75], v195 offset:49152
	ds_read_b128 v[182:185], v195 offset:50176
	ds_read_b128 v[186:189], v195 offset:51200
	ds_read_b128 v[190:193], v195 offset:52224
	ds_read_b128 v[196:199], v195 offset:53248
	ds_read_b128 v[200:203], v195 offset:54272
	ds_read_b128 v[204:207], v195 offset:55296
	ds_read_b128 v[210:213], v195 offset:56320
	global_load_lds_dwordx4 v208, s[48:49]
	s_add_i32 m0, s26, 0x2000
	s_add_u32 s22, s22, 0x80080
	s_addc_u32 s23, s23, 0
	s_add_i32 s26, s81, s47
	global_load_lds_dwordx4 v160, s[48:49]
	s_mov_b32 m0, s26
	s_nop 0
	global_load_lds_dwordx4 v208, s[22:23]
	s_add_i32 m0, s26, 0x2000
	s_nop 0
	global_load_lds_dwordx4 v160, s[22:23]
	s_mov_b32 m0, s73
	s_nop 0
	global_load_lds_dwordx4 v164, s[98:99]
	s_mov_b32 m0, s74
	s_nop 0
	global_load_lds_dwordx4 v162, s[98:99]
	s_waitcnt vmcnt(8) lgkmcnt(0)
	s_setprio 1
	s_barrier
	v_mfma_f32_16x16x32_bf16 v[80:83], v[44:47], v[72:75], v[92:95]
	v_mfma_f32_16x16x32_bf16 v[92:95], v[52:55], v[182:185], v[80:83]
	v_mfma_f32_16x16x32_bf16 v[80:83], v[56:59], v[72:75], v[88:91]
	v_mfma_f32_16x16x32_bf16 v[88:91], v[60:63], v[182:185], v[80:83]
	v_mfma_f32_16x16x32_bf16 v[80:83], v[44:47], v[186:189], v[84:87]
	v_mfma_f32_16x16x32_bf16 v[76:79], v[56:59], v[186:189], v[76:79]
	v_mfma_f32_16x16x32_bf16 v[48:51], v[44:47], v[196:199], v[48:51]
	v_mfma_f32_16x16x32_bf16 v[28:31], v[56:59], v[196:199], v[28:31]
	v_mfma_f32_16x16x32_bf16 v[16:19], v[44:47], v[204:207], v[16:19]
	v_mfma_f32_16x16x32_bf16 v[8:11], v[56:59], v[204:207], v[8:11]
	v_mfma_f32_16x16x32_bf16 v[84:87], v[52:55], v[190:193], v[80:83]
	v_mfma_f32_16x16x32_bf16 v[76:79], v[60:63], v[190:193], v[76:79]
	v_mfma_f32_16x16x32_bf16 v[48:51], v[52:55], v[200:203], v[48:51]
	v_mfma_f32_16x16x32_bf16 v[28:31], v[60:63], v[200:203], v[28:31]
	v_mfma_f32_16x16x32_bf16 v[16:19], v[52:55], v[210:213], v[16:19]
	v_mfma_f32_16x16x32_bf16 v[8:11], v[60:63], v[210:213], v[8:11]
	v_mfma_f32_16x16x32_bf16 v[24:27], v[64:67], v[72:75], v[24:27]
	v_mfma_f32_16x16x32_bf16 v[80:83], v[68:71], v[182:185], v[24:27]
	v_mfma_f32_16x16x32_bf16 v[24:27], v[174:177], v[72:75], v[36:39]
	v_mfma_f32_16x16x32_bf16 v[72:75], v[178:181], v[182:185], v[24:27]
	v_mfma_f32_16x16x32_bf16 v[24:27], v[64:67], v[186:189], v[32:35]
	v_mfma_f32_16x16x32_bf16 v[32:35], v[68:71], v[190:193], v[24:27]
	v_mfma_f32_16x16x32_bf16 v[24:27], v[174:177], v[186:189], v[40:43]
	v_mfma_f32_16x16x32_bf16 v[12:15], v[64:67], v[196:199], v[12:15]
	v_mfma_f32_16x16x32_bf16 v[20:23], v[174:177], v[196:199], v[20:23]
	v_mfma_f32_16x16x32_bf16 v[0:3], v[64:67], v[204:207], v[0:3]
	v_mfma_f32_16x16x32_bf16 v[4:7], v[174:177], v[204:207], v[4:7]
	v_mfma_f32_16x16x32_bf16 v[56:59], v[178:181], v[190:193], v[24:27]
	v_mfma_f32_16x16x32_bf16 v[12:15], v[68:71], v[200:203], v[12:15]
	v_mfma_f32_16x16x32_bf16 v[20:23], v[178:181], v[200:203], v[20:23]
	v_mfma_f32_16x16x32_bf16 v[0:3], v[68:71], v[210:213], v[0:3]
	v_mfma_f32_16x16x32_bf16 v[4:7], v[178:181], v[210:213], v[4:7]
	s_barrier
	s_setprio 0
	s_add_i32 s79, s79, 2
	s_add_u32 vcc_lo, vcc_lo, 0x100
	s_addc_u32 vcc_hi, vcc_hi, 0
	s_add_u32 s77, s77, 0x100
	s_addc_u32 s78, s78, 0
	s_cmp_gt_u32 s79, 29
	s_cbranch_scc0 .LBB0_479
	s_and_b64 vcc, exec, s[60:61]
	s_cbranch_vccz .LBB0_482
	s_barrier
